# s5 unit epilogue: gelu_tanh as packed f32 pairs (same op sequence), 16 dwordx2 row-per-lane stores -> 8 dwordx4 via permlane32_swap
# speedup vs baseline: 1.0113x; 1.0027x over previous
.LBB0_718:
	s_and_b32 s7, s17, 31
	s_add_i32 s88, s16, s7
	s_and_b32 s23, s6, 31
	s_lshl_b64 s[8:9], s[88:89], 18
	s_or_b32 s88, s23, s16
	s_ashr_i32 s7, s6, 31
	s_lshl_b64 s[10:11], s[88:89], 18
	s_lshl_b64 s[24:25], s[6:7], 16
	s_add_u32 s24, s12, s24
	s_addc_u32 s25, s13, s25
	v_lshl_add_u64 v[0:1], s[24:25], 0, v[120:121]
	s_barrier
	global_load_dwordx4 v[0:3], v[0:1], off
	v_lshl_add_u64 v[4:5], s[24:25], 0, v[122:123]
	global_load_dwordx4 v[4:7], v[4:5], off
	v_lshl_add_u64 v[8:9], s[24:25], 0, v[124:125]
	global_load_dwordx4 v[8:11], v[8:9], off
	v_lshl_add_u64 v[12:13], s[24:25], 0, v[126:127]
	global_load_dwordx4 v[12:15], v[12:13], off
	v_lshl_add_u64 v[16:17], s[24:25], 0, v[128:129]
	global_load_dwordx4 v[16:19], v[16:17], off
	v_lshl_add_u64 v[20:21], s[24:25], 0, v[130:131]
	global_load_dwordx4 v[20:23], v[20:21], off
	v_lshl_add_u64 v[24:25], s[24:25], 0, v[132:133]
	global_load_dwordx4 v[24:27], v[24:25], off
	v_lshl_add_u64 v[28:29], s[24:25], 0, v[134:135]
	global_load_dwordx4 v[28:31], v[28:29], off
	v_mov_b32_e32 v32, v33
	v_mov_b32_e32 v46, v33
	v_mov_b32_e32 v47, v33
	s_lshl_b64 s[24:25], s[88:89], 17
	s_waitcnt vmcnt(12)
	v_mov_b32_e32 v34, v33
	v_mov_b32_e32 v35, v33
	v_mov_b32_e32 v36, v33
	v_mov_b32_e32 v37, v33
	s_waitcnt vmcnt(12)
	v_mov_b32_e32 v38, v33
	v_mov_b32_e32 v39, v33
	v_mov_b32_e32 v40, v33
	v_mov_b32_e32 v41, v33
	v_mov_b32_e32 v42, v33
	v_mov_b32_e32 v43, v33
	v_mov_b32_e32 v44, v33
	v_mov_b32_e32 v45, v33
	s_waitcnt vmcnt(10)
	v_mov_b64_e32 v[78:79], v[46:47]
	v_mov_b64_e32 v[62:63], v[46:47]
	v_lshl_add_u64 v[148:149], v[112:113], 0, s[10:11]
	v_lshl_add_u64 v[150:151], v[116:117], 0, s[24:25]
	v_lshl_add_u32 v147, s88, 8, v143
	v_lshl_add_u64 v[152:153], v[144:145], 0, s[8:9]
	s_mov_b32 s88, 0
	s_mov_b64 s[10:11], -1
	v_mov_b64_e32 v[76:77], v[44:45]
	v_mov_b64_e32 v[74:75], v[42:43]
	v_mov_b64_e32 v[72:73], v[40:41]
	v_mov_b64_e32 v[70:71], v[38:39]
	v_mov_b64_e32 v[68:69], v[36:37]
	v_mov_b64_e32 v[66:67], v[34:35]
	v_mov_b64_e32 v[64:65], v[32:33]
	v_mov_b64_e32 v[60:61], v[44:45]
	v_mov_b64_e32 v[58:59], v[42:43]
	v_mov_b64_e32 v[56:57], v[40:41]
	v_mov_b64_e32 v[54:55], v[38:39]
	v_mov_b64_e32 v[52:53], v[36:37]
	v_mov_b64_e32 v[50:51], v[34:35]
	v_mov_b64_e32 v[48:49], v[32:33]
	s_waitcnt vmcnt(7)
	ds_write_b128 v157, v[0:3]
	s_waitcnt vmcnt(6)
	ds_write_b128 v158, v[4:7]
	s_waitcnt vmcnt(5)
	ds_write_b128 v159, v[8:11]
	s_waitcnt vmcnt(4)
	ds_write_b128 v160, v[12:15]
	s_waitcnt vmcnt(3)
	ds_write_b128 v161, v[16:19]
	s_waitcnt vmcnt(2)
	ds_write_b128 v162, v[20:23]
	s_waitcnt vmcnt(1)
	ds_write_b128 v163, v[24:27]
	s_waitcnt vmcnt(0)
	ds_write_b128 v164, v[28:31]
	v_mov_b64_e32 v[16:17], v[32:33]
	v_mov_b64_e32 v[0:1], v[32:33]
	v_mov_b64_e32 v[18:19], v[34:35]
	v_mov_b64_e32 v[20:21], v[36:37]
	v_mov_b64_e32 v[22:23], v[38:39]
	v_mov_b64_e32 v[24:25], v[40:41]
	v_mov_b64_e32 v[26:27], v[42:43]
	v_mov_b64_e32 v[28:29], v[44:45]
	v_mov_b64_e32 v[30:31], v[46:47]
	v_mov_b64_e32 v[2:3], v[34:35]
	v_mov_b64_e32 v[4:5], v[36:37]
	v_mov_b64_e32 v[6:7], v[38:39]
	v_mov_b64_e32 v[8:9], v[40:41]
	v_mov_b64_e32 v[10:11], v[42:43]
	v_mov_b64_e32 v[12:13], v[44:45]
	v_mov_b64_e32 v[14:15], v[46:47]
	s_waitcnt lgkmcnt(0)
	s_barrier

.LBB0_724:
	s_lshl_b32 s24, s88, 6
	v_mov_b32_e32 v38, s24
	v_mov_b32_e32 v39, v33
	v_lshl_add_u64 v[38:39], v[152:153], 0, v[38:39]
	global_load_dwordx4 v[100:103], v[38:39], off offset:-4096
	global_load_dwordx4 v[104:107], v[38:39], off offset:-3072
	global_load_dwordx4 v[108:111], v[38:39], off offset:-2048
	global_load_dwordx4 v[166:169], v[38:39], off offset:-1024
	global_load_dwordx4 v[170:173], v[38:39], off
	global_load_dwordx4 v[174:177], v[38:39], off offset:1024
	global_load_dwordx4 v[190:193], v[38:39], off offset:2048
	global_load_dwordx4 v[194:197], v[38:39], off offset:3072
	v_add_u32_e32 v32, 0x10800, v156
	s_waitcnt lgkmcnt(0)
	s_barrier
	ds_read_b128 v[198:201], v32
	ds_read_b128 v[202:205], v32 offset:16
	ds_read_b128 v[206:209], v32 offset:16896
	ds_read_b128 v[234:237], v32 offset:16912
	ds_read_b128 v[238:241], v32 offset:33792
	ds_read_b128 v[242:245], v32 offset:33808
	s_waitcnt vmcnt(7) lgkmcnt(4)
	v_cvt_pk_bf16_f32 v246, v198, v199
	v_cvt_pk_bf16_f32 v247, v200, v201
	v_cvt_pk_bf16_f32 v248, v202, v203
	v_cvt_pk_bf16_f32 v249, v204, v205
	s_nop 1
	v_mfma_f32_32x32x16_bf16 v[64:79], v[100:103], v[246:249], v[64:79]
	ds_read_b128 v[198:201], v32 offset:50688
	ds_read_b128 v[202:205], v32 offset:50704
	s_waitcnt lgkmcnt(4)
	v_cvt_pk_bf16_f32 v250, v206, v207
	v_cvt_pk_bf16_f32 v251, v208, v209
	v_cvt_pk_bf16_f32 v252, v234, v235
	v_cvt_pk_bf16_f32 v253, v236, v237
	s_nop 1
	v_mfma_f32_32x32x16_bf16 v[48:63], v[100:103], v[250:253], v[48:63]
	ds_read_b128 v[206:209], v32 offset:64
	ds_read_b128 v[234:237], v32 offset:80
	s_waitcnt lgkmcnt(4)
	v_cvt_pk_bf16_f32 v246, v238, v239
	v_cvt_pk_bf16_f32 v247, v240, v241
	v_cvt_pk_bf16_f32 v248, v242, v243
	v_cvt_pk_bf16_f32 v249, v244, v245
	s_nop 1
	v_mfma_f32_32x32x16_bf16 v[16:31], v[100:103], v[246:249], v[16:31]
	ds_read_b128 v[238:241], v32 offset:16960
	ds_read_b128 v[242:245], v32 offset:16976
	s_waitcnt lgkmcnt(4)
	v_cvt_pk_bf16_f32 v250, v198, v199
	v_cvt_pk_bf16_f32 v251, v200, v201
	v_cvt_pk_bf16_f32 v252, v202, v203
	v_cvt_pk_bf16_f32 v253, v204, v205
	s_nop 1
	v_mfma_f32_32x32x16_bf16 v[0:15], v[100:103], v[250:253], v[0:15]
	ds_read_b128 v[198:201], v32 offset:33856
	ds_read_b128 v[202:205], v32 offset:33872
	s_waitcnt vmcnt(6) lgkmcnt(4)
	v_cvt_pk_bf16_f32 v246, v206, v207
	v_cvt_pk_bf16_f32 v247, v208, v209
	v_cvt_pk_bf16_f32 v248, v234, v235
	v_cvt_pk_bf16_f32 v249, v236, v237
	s_nop 1
	v_mfma_f32_32x32x16_bf16 v[64:79], v[104:107], v[246:249], v[64:79]
	ds_read_b128 v[206:209], v32 offset:50752
	ds_read_b128 v[234:237], v32 offset:50768
	s_waitcnt lgkmcnt(4)
	v_cvt_pk_bf16_f32 v250, v238, v239
	v_cvt_pk_bf16_f32 v251, v240, v241
	v_cvt_pk_bf16_f32 v252, v242, v243
	v_cvt_pk_bf16_f32 v253, v244, v245
	s_nop 1
	v_mfma_f32_32x32x16_bf16 v[48:63], v[104:107], v[250:253], v[48:63]
	ds_read_b128 v[238:241], v32 offset:128
	ds_read_b128 v[242:245], v32 offset:144
	s_waitcnt lgkmcnt(4)
	v_cvt_pk_bf16_f32 v246, v198, v199
	v_cvt_pk_bf16_f32 v247, v200, v201
	v_cvt_pk_bf16_f32 v248, v202, v203
	v_cvt_pk_bf16_f32 v249, v204, v205
	s_nop 1
	v_mfma_f32_32x32x16_bf16 v[16:31], v[104:107], v[246:249], v[16:31]
	ds_read_b128 v[198:201], v32 offset:17024
	ds_read_b128 v[202:205], v32 offset:17040
	s_waitcnt lgkmcnt(4)
	v_cvt_pk_bf16_f32 v250, v206, v207
	v_cvt_pk_bf16_f32 v251, v208, v209
	v_cvt_pk_bf16_f32 v252, v234, v235
	v_cvt_pk_bf16_f32 v253, v236, v237
	s_nop 1
	v_mfma_f32_32x32x16_bf16 v[0:15], v[104:107], v[250:253], v[0:15]
	ds_read_b128 v[206:209], v32 offset:33920
	ds_read_b128 v[234:237], v32 offset:33936
	s_waitcnt vmcnt(5) lgkmcnt(4)
	v_cvt_pk_bf16_f32 v246, v238, v239
	v_cvt_pk_bf16_f32 v247, v240, v241
	v_cvt_pk_bf16_f32 v248, v242, v243
	v_cvt_pk_bf16_f32 v249, v244, v245
	s_nop 1
	v_mfma_f32_32x32x16_bf16 v[64:79], v[108:111], v[246:249], v[64:79]
	ds_read_b128 v[238:241], v32 offset:50816
	ds_read_b128 v[242:245], v32 offset:50832
	s_waitcnt lgkmcnt(4)
	v_cvt_pk_bf16_f32 v250, v198, v199
	v_cvt_pk_bf16_f32 v251, v200, v201
	v_cvt_pk_bf16_f32 v252, v202, v203
	v_cvt_pk_bf16_f32 v253, v204, v205
	s_nop 1
	v_mfma_f32_32x32x16_bf16 v[48:63], v[108:111], v[250:253], v[48:63]
	ds_read_b128 v[198:201], v32 offset:192
	ds_read_b128 v[202:205], v32 offset:208
	s_waitcnt lgkmcnt(4)
	v_cvt_pk_bf16_f32 v246, v206, v207
	v_cvt_pk_bf16_f32 v247, v208, v209
	v_cvt_pk_bf16_f32 v248, v234, v235
	v_cvt_pk_bf16_f32 v249, v236, v237
	s_nop 1
	v_mfma_f32_32x32x16_bf16 v[16:31], v[108:111], v[246:249], v[16:31]
	ds_read_b128 v[206:209], v32 offset:17088
	ds_read_b128 v[234:237], v32 offset:17104
	s_waitcnt lgkmcnt(4)
	v_cvt_pk_bf16_f32 v250, v238, v239
	v_cvt_pk_bf16_f32 v251, v240, v241
	v_cvt_pk_bf16_f32 v252, v242, v243
	v_cvt_pk_bf16_f32 v253, v244, v245
	s_nop 1
	v_mfma_f32_32x32x16_bf16 v[0:15], v[108:111], v[250:253], v[0:15]
	ds_read_b128 v[238:241], v32 offset:33984
	ds_read_b128 v[242:245], v32 offset:34000
	s_waitcnt vmcnt(4) lgkmcnt(4)
	v_cvt_pk_bf16_f32 v246, v198, v199
	v_cvt_pk_bf16_f32 v247, v200, v201
	v_cvt_pk_bf16_f32 v248, v202, v203
	v_cvt_pk_bf16_f32 v249, v204, v205
	s_nop 1
	v_mfma_f32_32x32x16_bf16 v[64:79], v[166:169], v[246:249], v[64:79]
	ds_read_b128 v[198:201], v32 offset:50880
	ds_read_b128 v[202:205], v32 offset:50896
	s_waitcnt lgkmcnt(4)
	v_cvt_pk_bf16_f32 v250, v206, v207
	v_cvt_pk_bf16_f32 v251, v208, v209
	v_cvt_pk_bf16_f32 v252, v234, v235
	v_cvt_pk_bf16_f32 v253, v236, v237
	s_nop 1
	v_mfma_f32_32x32x16_bf16 v[48:63], v[166:169], v[250:253], v[48:63]
	ds_read_b128 v[206:209], v32 offset:256
	ds_read_b128 v[234:237], v32 offset:272
	s_waitcnt lgkmcnt(4)
	v_cvt_pk_bf16_f32 v246, v238, v239
	v_cvt_pk_bf16_f32 v247, v240, v241
	v_cvt_pk_bf16_f32 v248, v242, v243
	v_cvt_pk_bf16_f32 v249, v244, v245
	s_nop 1
	v_mfma_f32_32x32x16_bf16 v[16:31], v[166:169], v[246:249], v[16:31]
	ds_read_b128 v[238:241], v32 offset:17152
	ds_read_b128 v[242:245], v32 offset:17168
	s_waitcnt lgkmcnt(4)
	v_cvt_pk_bf16_f32 v250, v198, v199
	v_cvt_pk_bf16_f32 v251, v200, v201
	v_cvt_pk_bf16_f32 v252, v202, v203
	v_cvt_pk_bf16_f32 v253, v204, v205
	s_nop 1
	v_mfma_f32_32x32x16_bf16 v[0:15], v[166:169], v[250:253], v[0:15]
	ds_read_b128 v[198:201], v32 offset:34048
	ds_read_b128 v[202:205], v32 offset:34064
	s_waitcnt vmcnt(3) lgkmcnt(4)
	v_cvt_pk_bf16_f32 v246, v206, v207
	v_cvt_pk_bf16_f32 v247, v208, v209
	v_cvt_pk_bf16_f32 v248, v234, v235
	v_cvt_pk_bf16_f32 v249, v236, v237
	s_nop 1
	v_mfma_f32_32x32x16_bf16 v[64:79], v[170:173], v[246:249], v[64:79]
	ds_read_b128 v[206:209], v32 offset:50944
	ds_read_b128 v[234:237], v32 offset:50960
	s_waitcnt lgkmcnt(4)
	v_cvt_pk_bf16_f32 v250, v238, v239
	v_cvt_pk_bf16_f32 v251, v240, v241
	v_cvt_pk_bf16_f32 v252, v242, v243
	v_cvt_pk_bf16_f32 v253, v244, v245
	s_nop 1
	v_mfma_f32_32x32x16_bf16 v[48:63], v[170:173], v[250:253], v[48:63]
	ds_read_b128 v[238:241], v32 offset:320
	ds_read_b128 v[242:245], v32 offset:336
	s_waitcnt lgkmcnt(4)
	v_cvt_pk_bf16_f32 v246, v198, v199
	v_cvt_pk_bf16_f32 v247, v200, v201
	v_cvt_pk_bf16_f32 v248, v202, v203
	v_cvt_pk_bf16_f32 v249, v204, v205
	s_nop 1
	v_mfma_f32_32x32x16_bf16 v[16:31], v[170:173], v[246:249], v[16:31]
	ds_read_b128 v[198:201], v32 offset:17216
	ds_read_b128 v[202:205], v32 offset:17232
	s_waitcnt lgkmcnt(4)
	v_cvt_pk_bf16_f32 v250, v206, v207
	v_cvt_pk_bf16_f32 v251, v208, v209
	v_cvt_pk_bf16_f32 v252, v234, v235
	v_cvt_pk_bf16_f32 v253, v236, v237
	s_nop 1
	v_mfma_f32_32x32x16_bf16 v[0:15], v[170:173], v[250:253], v[0:15]
	ds_read_b128 v[206:209], v32 offset:34112
	ds_read_b128 v[234:237], v32 offset:34128
	s_waitcnt vmcnt(2) lgkmcnt(4)
	v_cvt_pk_bf16_f32 v246, v238, v239
	v_cvt_pk_bf16_f32 v247, v240, v241
	v_cvt_pk_bf16_f32 v248, v242, v243
	v_cvt_pk_bf16_f32 v249, v244, v245
	s_nop 1
	v_mfma_f32_32x32x16_bf16 v[64:79], v[174:177], v[246:249], v[64:79]
	ds_read_b128 v[238:241], v32 offset:51008
	ds_read_b128 v[242:245], v32 offset:51024
	s_waitcnt lgkmcnt(4)
	v_cvt_pk_bf16_f32 v250, v198, v199
	v_cvt_pk_bf16_f32 v251, v200, v201
	v_cvt_pk_bf16_f32 v252, v202, v203
	v_cvt_pk_bf16_f32 v253, v204, v205
	s_nop 1
	v_mfma_f32_32x32x16_bf16 v[48:63], v[174:177], v[250:253], v[48:63]
	ds_read_b128 v[198:201], v32 offset:384
	ds_read_b128 v[202:205], v32 offset:400
	s_waitcnt lgkmcnt(4)
	v_cvt_pk_bf16_f32 v246, v206, v207
	v_cvt_pk_bf16_f32 v247, v208, v209
	v_cvt_pk_bf16_f32 v248, v234, v235
	v_cvt_pk_bf16_f32 v249, v236, v237
	s_nop 1
	v_mfma_f32_32x32x16_bf16 v[16:31], v[174:177], v[246:249], v[16:31]
	ds_read_b128 v[206:209], v32 offset:17280
	ds_read_b128 v[234:237], v32 offset:17296
	s_waitcnt lgkmcnt(4)
	v_cvt_pk_bf16_f32 v250, v238, v239
	v_cvt_pk_bf16_f32 v251, v240, v241
	v_cvt_pk_bf16_f32 v252, v242, v243
	v_cvt_pk_bf16_f32 v253, v244, v245
	s_nop 1
	v_mfma_f32_32x32x16_bf16 v[0:15], v[174:177], v[250:253], v[0:15]
	ds_read_b128 v[238:241], v32 offset:34176
	ds_read_b128 v[242:245], v32 offset:34192
	s_waitcnt vmcnt(1) lgkmcnt(4)
	v_cvt_pk_bf16_f32 v246, v198, v199
	v_cvt_pk_bf16_f32 v247, v200, v201
	v_cvt_pk_bf16_f32 v248, v202, v203
	v_cvt_pk_bf16_f32 v249, v204, v205
	s_nop 1
	v_mfma_f32_32x32x16_bf16 v[64:79], v[190:193], v[246:249], v[64:79]
	ds_read_b128 v[198:201], v32 offset:51072
	ds_read_b128 v[202:205], v32 offset:51088
	s_waitcnt lgkmcnt(4)
	v_cvt_pk_bf16_f32 v250, v206, v207
	v_cvt_pk_bf16_f32 v251, v208, v209
	v_cvt_pk_bf16_f32 v252, v234, v235
	v_cvt_pk_bf16_f32 v253, v236, v237
	s_nop 1
	v_mfma_f32_32x32x16_bf16 v[48:63], v[190:193], v[250:253], v[48:63]
	ds_read_b128 v[206:209], v32 offset:448
	ds_read_b128 v[234:237], v32 offset:464
	s_waitcnt lgkmcnt(4)
	v_cvt_pk_bf16_f32 v246, v238, v239
	v_cvt_pk_bf16_f32 v247, v240, v241
	v_cvt_pk_bf16_f32 v248, v242, v243
	v_cvt_pk_bf16_f32 v249, v244, v245
	s_nop 1
	v_mfma_f32_32x32x16_bf16 v[16:31], v[190:193], v[246:249], v[16:31]
	ds_read_b128 v[238:241], v32 offset:17344
	ds_read_b128 v[242:245], v32 offset:17360
	s_waitcnt lgkmcnt(4)
	v_cvt_pk_bf16_f32 v250, v198, v199
	v_cvt_pk_bf16_f32 v251, v200, v201
	v_cvt_pk_bf16_f32 v252, v202, v203
	v_cvt_pk_bf16_f32 v253, v204, v205
	s_nop 1
	v_mfma_f32_32x32x16_bf16 v[0:15], v[190:193], v[250:253], v[0:15]
	ds_read_b128 v[198:201], v32 offset:34240
	ds_read_b128 v[202:205], v32 offset:34256
	s_waitcnt vmcnt(0) lgkmcnt(4)
	v_cvt_pk_bf16_f32 v246, v206, v207
	v_cvt_pk_bf16_f32 v247, v208, v209
	v_cvt_pk_bf16_f32 v248, v234, v235
	v_cvt_pk_bf16_f32 v249, v236, v237
	s_nop 1
	v_mfma_f32_32x32x16_bf16 v[64:79], v[194:197], v[246:249], v[64:79]
	ds_read_b128 v[206:209], v32 offset:51136
	ds_read_b128 v[234:237], v32 offset:51152
	s_waitcnt lgkmcnt(4)
	v_cvt_pk_bf16_f32 v250, v238, v239
	v_cvt_pk_bf16_f32 v251, v240, v241
	v_cvt_pk_bf16_f32 v252, v242, v243
	v_cvt_pk_bf16_f32 v253, v244, v245
	s_nop 1
	v_mfma_f32_32x32x16_bf16 v[48:63], v[194:197], v[250:253], v[48:63]
	s_waitcnt lgkmcnt(2)
	v_cvt_pk_bf16_f32 v246, v198, v199
	v_cvt_pk_bf16_f32 v247, v200, v201
	v_cvt_pk_bf16_f32 v248, v202, v203
	v_cvt_pk_bf16_f32 v249, v204, v205
	s_nop 1
	v_mfma_f32_32x32x16_bf16 v[16:31], v[194:197], v[246:249], v[16:31]
	s_waitcnt lgkmcnt(0)
	v_cvt_pk_bf16_f32 v250, v206, v207
	v_cvt_pk_bf16_f32 v251, v208, v209
	v_cvt_pk_bf16_f32 v252, v234, v235
	v_cvt_pk_bf16_f32 v253, v236, v237
	s_nop 1
	v_mfma_f32_32x32x16_bf16 v[0:15], v[194:197], v[250:253], v[0:15]
	s_movk_i32 s88, 0x80
	s_mov_b64 s[10:11], 0
	s_and_b64 vcc, exec, s[8:9]
	s_barrier
	s_cbranch_vccz .LBB0_719
	s_ashr_i32 s8, s6, 5
	s_lshl_b32 s10, s8, 11
	s_lshl_b32 s7, s23, 5
	s_add_u32 s8, s14, s7
	s_addc_u32 s9, s15, 0
	v_or_b32_e32 v34, s10, v118
	v_add_u32_e32 v34, v34, v114
	v_lshlrev_b32_e32 v34, 10, v34
	v_bfe_u32 v35, v210, 5, 1
	v_lshl_add_u32 v34, v35, 4, v34
	v_mov_b32_e32 v35, 0
	v_lshl_add_u64 v[234:235], s[8:9], 0, v[34:35]
	v_mov_b32_e32 v34, 0x80000
	v_lshl_add_u64 v[236:237], v[234:235], 0, v[34:35]
	v_mov_b32_e32 v34, 0x100000
	v_lshl_add_u64 v[238:239], v[234:235], 0, v[34:35]
	v_mov_b32_e32 v34, 0x180000
	v_lshl_add_u64 v[240:241], v[234:235], 0, v[34:35]
	v_mov_b32_e32 v166, 0x3d372713
	v_mov_b32_e32 v167, 0x3d372713
	v_mov_b32_e32 v168, 0x3f4c422a
	v_mov_b32_e32 v169, 0x3f4c422a
	v_mov_b32_e32 v170, 0x3fb8aa3b
	v_mov_b32_e32 v171, 0x3fb8aa3b
	v_mov_b32_e32 v172, 0.5
	v_mov_b32_e32 v173, 0.5
	v_mov_b32_e32 v174, 1.0
	v_mov_b32_e32 v175, 1.0
	v_mov_b32_e32 v176, -2.0
	v_mov_b32_e32 v177, -2.0
	s_add_i32 s6, s6, s28
	s_add_i32 s17, s17, s28
	v_pk_mul_f32 v[190:191], v[166:167], v[64:65]
	v_pk_mul_f32 v[192:193], v[166:167], v[66:67]
	v_pk_mul_f32 v[194:195], v[166:167], v[68:69]
	v_pk_mul_f32 v[196:197], v[166:167], v[70:71]
	v_pk_mul_f32 v[190:191], v[64:65], v[190:191]
	v_pk_mul_f32 v[192:193], v[66:67], v[192:193]
	v_pk_mul_f32 v[194:195], v[68:69], v[194:195]
	v_pk_mul_f32 v[196:197], v[70:71], v[196:197]
	v_pk_fma_f32 v[190:191], v[64:65], v[190:191], v[64:65]
	v_pk_fma_f32 v[192:193], v[66:67], v[192:193], v[66:67]
	v_pk_fma_f32 v[194:195], v[68:69], v[194:195], v[68:69]
	v_pk_fma_f32 v[196:197], v[70:71], v[196:197], v[70:71]
	v_pk_mul_f32 v[190:191], v[168:169], v[190:191]
	v_pk_mul_f32 v[192:193], v[168:169], v[192:193]
	v_pk_mul_f32 v[194:195], v[168:169], v[194:195]
	v_pk_mul_f32 v[196:197], v[168:169], v[196:197]
	v_pk_add_f32 v[190:191], v[190:191], v[190:191]
	v_pk_add_f32 v[192:193], v[192:193], v[192:193]
	v_pk_add_f32 v[194:195], v[194:195], v[194:195]
	v_pk_add_f32 v[196:197], v[196:197], v[196:197]
	v_pk_mul_f32 v[190:191], v[170:171], v[190:191]
	v_pk_mul_f32 v[192:193], v[170:171], v[192:193]
	v_pk_mul_f32 v[194:195], v[170:171], v[194:195]
	v_pk_mul_f32 v[196:197], v[170:171], v[196:197]
	v_exp_f32_e32 v190, v190
	v_exp_f32_e32 v191, v191
	v_exp_f32_e32 v192, v192
	v_exp_f32_e32 v193, v193
	v_exp_f32_e32 v194, v194
	v_exp_f32_e32 v195, v195
	v_exp_f32_e32 v196, v196
	v_exp_f32_e32 v197, v197
	v_pk_mul_f32 v[64:65], v[172:173], v[64:65]
	v_pk_mul_f32 v[66:67], v[172:173], v[66:67]
	v_pk_mul_f32 v[68:69], v[172:173], v[68:69]
	v_pk_mul_f32 v[70:71], v[172:173], v[70:71]
	v_pk_add_f32 v[190:191], v[174:175], v[190:191]
	v_pk_add_f32 v[192:193], v[174:175], v[192:193]
	v_pk_add_f32 v[194:195], v[174:175], v[194:195]
	v_pk_add_f32 v[196:197], v[174:175], v[196:197]
	v_rcp_f32_e32 v190, v190
	v_rcp_f32_e32 v191, v191
	v_rcp_f32_e32 v192, v192
	v_rcp_f32_e32 v193, v193
	v_rcp_f32_e32 v194, v194
	v_rcp_f32_e32 v195, v195
	v_rcp_f32_e32 v196, v196
	v_rcp_f32_e32 v197, v197
	s_nop 0
	v_pk_fma_f32 v[190:191], v[190:191], v[176:177], v[174:175]
	v_pk_fma_f32 v[192:193], v[192:193], v[176:177], v[174:175]
	v_pk_fma_f32 v[194:195], v[194:195], v[176:177], v[174:175]
	v_pk_fma_f32 v[196:197], v[196:197], v[176:177], v[174:175]
	v_pk_add_f32 v[190:191], v[174:175], v[190:191]
	v_pk_add_f32 v[192:193], v[174:175], v[192:193]
	v_pk_add_f32 v[194:195], v[174:175], v[194:195]
	v_pk_add_f32 v[196:197], v[174:175], v[196:197]
	v_pk_mul_f32 v[64:65], v[64:65], v[190:191]
	v_pk_mul_f32 v[66:67], v[66:67], v[192:193]
	v_pk_mul_f32 v[68:69], v[68:69], v[194:195]
	v_pk_mul_f32 v[70:71], v[70:71], v[196:197]
	v_cvt_pk_bf16_f32 v198, v64, v65
	v_cvt_pk_bf16_f32 v199, v66, v67
	v_cvt_pk_bf16_f32 v200, v68, v69
	v_cvt_pk_bf16_f32 v201, v70, v71
	s_nop 1
	v_permlane32_swap_b32 v198, v200
	v_permlane32_swap_b32 v199, v201
	global_store_dwordx4 v[234:235], v[198:201], off
	v_pk_mul_f32 v[190:191], v[166:167], v[72:73]
	v_pk_mul_f32 v[192:193], v[166:167], v[74:75]
	v_pk_mul_f32 v[194:195], v[166:167], v[76:77]
	v_pk_mul_f32 v[196:197], v[166:167], v[78:79]
	v_pk_mul_f32 v[190:191], v[72:73], v[190:191]
	v_pk_mul_f32 v[192:193], v[74:75], v[192:193]
	v_pk_mul_f32 v[194:195], v[76:77], v[194:195]
	v_pk_mul_f32 v[196:197], v[78:79], v[196:197]
	v_pk_fma_f32 v[190:191], v[72:73], v[190:191], v[72:73]
	v_pk_fma_f32 v[192:193], v[74:75], v[192:193], v[74:75]
	v_pk_fma_f32 v[194:195], v[76:77], v[194:195], v[76:77]
	v_pk_fma_f32 v[196:197], v[78:79], v[196:197], v[78:79]
	v_pk_mul_f32 v[190:191], v[168:169], v[190:191]
	v_pk_mul_f32 v[192:193], v[168:169], v[192:193]
	v_pk_mul_f32 v[194:195], v[168:169], v[194:195]
	v_pk_mul_f32 v[196:197], v[168:169], v[196:197]
	v_pk_add_f32 v[190:191], v[190:191], v[190:191]
	v_pk_add_f32 v[192:193], v[192:193], v[192:193]
	v_pk_add_f32 v[194:195], v[194:195], v[194:195]
	v_pk_add_f32 v[196:197], v[196:197], v[196:197]
	v_pk_mul_f32 v[190:191], v[170:171], v[190:191]
	v_pk_mul_f32 v[192:193], v[170:171], v[192:193]
	v_pk_mul_f32 v[194:195], v[170:171], v[194:195]
	v_pk_mul_f32 v[196:197], v[170:171], v[196:197]
	v_exp_f32_e32 v190, v190
	v_exp_f32_e32 v191, v191
	v_exp_f32_e32 v192, v192
	v_exp_f32_e32 v193, v193
	v_exp_f32_e32 v194, v194
	v_exp_f32_e32 v195, v195
	v_exp_f32_e32 v196, v196
	v_exp_f32_e32 v197, v197
	v_pk_mul_f32 v[72:73], v[172:173], v[72:73]
	v_pk_mul_f32 v[74:75], v[172:173], v[74:75]
	v_pk_mul_f32 v[76:77], v[172:173], v[76:77]
	v_pk_mul_f32 v[78:79], v[172:173], v[78:79]
	v_pk_add_f32 v[190:191], v[174:175], v[190:191]
	v_pk_add_f32 v[192:193], v[174:175], v[192:193]
	v_pk_add_f32 v[194:195], v[174:175], v[194:195]
	v_pk_add_f32 v[196:197], v[174:175], v[196:197]
	v_rcp_f32_e32 v190, v190
	v_rcp_f32_e32 v191, v191
	v_rcp_f32_e32 v192, v192
	v_rcp_f32_e32 v193, v193
	v_rcp_f32_e32 v194, v194
	v_rcp_f32_e32 v195, v195
	v_rcp_f32_e32 v196, v196
	v_rcp_f32_e32 v197, v197
	s_nop 0
	v_pk_fma_f32 v[190:191], v[190:191], v[176:177], v[174:175]
	v_pk_fma_f32 v[192:193], v[192:193], v[176:177], v[174:175]
	v_pk_fma_f32 v[194:195], v[194:195], v[176:177], v[174:175]
	v_pk_fma_f32 v[196:197], v[196:197], v[176:177], v[174:175]
	v_pk_add_f32 v[190:191], v[174:175], v[190:191]
	v_pk_add_f32 v[192:193], v[174:175], v[192:193]
	v_pk_add_f32 v[194:195], v[174:175], v[194:195]
	v_pk_add_f32 v[196:197], v[174:175], v[196:197]
	v_pk_mul_f32 v[72:73], v[72:73], v[190:191]
	v_pk_mul_f32 v[74:75], v[74:75], v[192:193]
	v_pk_mul_f32 v[76:77], v[76:77], v[194:195]
	v_pk_mul_f32 v[78:79], v[78:79], v[196:197]
	v_cvt_pk_bf16_f32 v202, v72, v73
	v_cvt_pk_bf16_f32 v203, v74, v75
	v_cvt_pk_bf16_f32 v204, v76, v77
	v_cvt_pk_bf16_f32 v205, v78, v79
	s_nop 1
	v_permlane32_swap_b32 v202, v204
	v_permlane32_swap_b32 v203, v205
	global_store_dwordx4 v[234:235], v[202:205], off offset:1024
	v_pk_mul_f32 v[190:191], v[166:167], v[48:49]
	v_pk_mul_f32 v[192:193], v[166:167], v[50:51]
	v_pk_mul_f32 v[194:195], v[166:167], v[52:53]
	v_pk_mul_f32 v[196:197], v[166:167], v[54:55]
	v_pk_mul_f32 v[190:191], v[48:49], v[190:191]
	v_pk_mul_f32 v[192:193], v[50:51], v[192:193]
	v_pk_mul_f32 v[194:195], v[52:53], v[194:195]
	v_pk_mul_f32 v[196:197], v[54:55], v[196:197]
	v_pk_fma_f32 v[190:191], v[48:49], v[190:191], v[48:49]
	v_pk_fma_f32 v[192:193], v[50:51], v[192:193], v[50:51]
	v_pk_fma_f32 v[194:195], v[52:53], v[194:195], v[52:53]
	v_pk_fma_f32 v[196:197], v[54:55], v[196:197], v[54:55]
	v_pk_mul_f32 v[190:191], v[168:169], v[190:191]
	v_pk_mul_f32 v[192:193], v[168:169], v[192:193]
	v_pk_mul_f32 v[194:195], v[168:169], v[194:195]
	v_pk_mul_f32 v[196:197], v[168:169], v[196:197]
	v_pk_add_f32 v[190:191], v[190:191], v[190:191]
	v_pk_add_f32 v[192:193], v[192:193], v[192:193]
	v_pk_add_f32 v[194:195], v[194:195], v[194:195]
	v_pk_add_f32 v[196:197], v[196:197], v[196:197]
	v_pk_mul_f32 v[190:191], v[170:171], v[190:191]
	v_pk_mul_f32 v[192:193], v[170:171], v[192:193]
	v_pk_mul_f32 v[194:195], v[170:171], v[194:195]
	v_pk_mul_f32 v[196:197], v[170:171], v[196:197]
	v_exp_f32_e32 v190, v190
	v_exp_f32_e32 v191, v191
	v_exp_f32_e32 v192, v192
	v_exp_f32_e32 v193, v193
	v_exp_f32_e32 v194, v194
	v_exp_f32_e32 v195, v195
	v_exp_f32_e32 v196, v196
	v_exp_f32_e32 v197, v197
	v_pk_mul_f32 v[48:49], v[172:173], v[48:49]
	v_pk_mul_f32 v[50:51], v[172:173], v[50:51]
	v_pk_mul_f32 v[52:53], v[172:173], v[52:53]
	v_pk_mul_f32 v[54:55], v[172:173], v[54:55]
	v_pk_add_f32 v[190:191], v[174:175], v[190:191]
	v_pk_add_f32 v[192:193], v[174:175], v[192:193]
	v_pk_add_f32 v[194:195], v[174:175], v[194:195]
	v_pk_add_f32 v[196:197], v[174:175], v[196:197]
	v_rcp_f32_e32 v190, v190
	v_rcp_f32_e32 v191, v191
	v_rcp_f32_e32 v192, v192
	v_rcp_f32_e32 v193, v193
	v_rcp_f32_e32 v194, v194
	v_rcp_f32_e32 v195, v195
	v_rcp_f32_e32 v196, v196
	v_rcp_f32_e32 v197, v197
	s_nop 0
	v_pk_fma_f32 v[190:191], v[190:191], v[176:177], v[174:175]
	v_pk_fma_f32 v[192:193], v[192:193], v[176:177], v[174:175]
	v_pk_fma_f32 v[194:195], v[194:195], v[176:177], v[174:175]
	v_pk_fma_f32 v[196:197], v[196:197], v[176:177], v[174:175]
	v_pk_add_f32 v[190:191], v[174:175], v[190:191]
	v_pk_add_f32 v[192:193], v[174:175], v[192:193]
	v_pk_add_f32 v[194:195], v[174:175], v[194:195]
	v_pk_add_f32 v[196:197], v[174:175], v[196:197]
	v_pk_mul_f32 v[48:49], v[48:49], v[190:191]
	v_pk_mul_f32 v[50:51], v[50:51], v[192:193]
	v_pk_mul_f32 v[52:53], v[52:53], v[194:195]
	v_pk_mul_f32 v[54:55], v[54:55], v[196:197]
	v_cvt_pk_bf16_f32 v198, v48, v49
	v_cvt_pk_bf16_f32 v199, v50, v51
	v_cvt_pk_bf16_f32 v200, v52, v53
	v_cvt_pk_bf16_f32 v201, v54, v55
	s_nop 1
	v_permlane32_swap_b32 v198, v200
	v_permlane32_swap_b32 v199, v201
	global_store_dwordx4 v[236:237], v[198:201], off
	v_pk_mul_f32 v[190:191], v[166:167], v[56:57]
	v_pk_mul_f32 v[192:193], v[166:167], v[58:59]
	v_pk_mul_f32 v[194:195], v[166:167], v[60:61]
	v_pk_mul_f32 v[196:197], v[166:167], v[62:63]
	v_pk_mul_f32 v[190:191], v[56:57], v[190:191]
	v_pk_mul_f32 v[192:193], v[58:59], v[192:193]
	v_pk_mul_f32 v[194:195], v[60:61], v[194:195]
	v_pk_mul_f32 v[196:197], v[62:63], v[196:197]
	v_pk_fma_f32 v[190:191], v[56:57], v[190:191], v[56:57]
	v_pk_fma_f32 v[192:193], v[58:59], v[192:193], v[58:59]
	v_pk_fma_f32 v[194:195], v[60:61], v[194:195], v[60:61]
	v_pk_fma_f32 v[196:197], v[62:63], v[196:197], v[62:63]
	v_pk_mul_f32 v[190:191], v[168:169], v[190:191]
	v_pk_mul_f32 v[192:193], v[168:169], v[192:193]
	v_pk_mul_f32 v[194:195], v[168:169], v[194:195]
	v_pk_mul_f32 v[196:197], v[168:169], v[196:197]
	v_pk_add_f32 v[190:191], v[190:191], v[190:191]
	v_pk_add_f32 v[192:193], v[192:193], v[192:193]
	v_pk_add_f32 v[194:195], v[194:195], v[194:195]
	v_pk_add_f32 v[196:197], v[196:197], v[196:197]
	v_pk_mul_f32 v[190:191], v[170:171], v[190:191]
	v_pk_mul_f32 v[192:193], v[170:171], v[192:193]
	v_pk_mul_f32 v[194:195], v[170:171], v[194:195]
	v_pk_mul_f32 v[196:197], v[170:171], v[196:197]
	v_exp_f32_e32 v190, v190
	v_exp_f32_e32 v191, v191
	v_exp_f32_e32 v192, v192
	v_exp_f32_e32 v193, v193
	v_exp_f32_e32 v194, v194
	v_exp_f32_e32 v195, v195
	v_exp_f32_e32 v196, v196
	v_exp_f32_e32 v197, v197
	v_pk_mul_f32 v[56:57], v[172:173], v[56:57]
	v_pk_mul_f32 v[58:59], v[172:173], v[58:59]
	v_pk_mul_f32 v[60:61], v[172:173], v[60:61]
	v_pk_mul_f32 v[62:63], v[172:173], v[62:63]
	v_pk_add_f32 v[190:191], v[174:175], v[190:191]
	v_pk_add_f32 v[192:193], v[174:175], v[192:193]
	v_pk_add_f32 v[194:195], v[174:175], v[194:195]
	v_pk_add_f32 v[196:197], v[174:175], v[196:197]
	v_rcp_f32_e32 v190, v190
	v_rcp_f32_e32 v191, v191
	v_rcp_f32_e32 v192, v192
	v_rcp_f32_e32 v193, v193
	v_rcp_f32_e32 v194, v194
	v_rcp_f32_e32 v195, v195
	v_rcp_f32_e32 v196, v196
	v_rcp_f32_e32 v197, v197
	s_nop 0
	v_pk_fma_f32 v[190:191], v[190:191], v[176:177], v[174:175]
	v_pk_fma_f32 v[192:193], v[192:193], v[176:177], v[174:175]
	v_pk_fma_f32 v[194:195], v[194:195], v[176:177], v[174:175]
	v_pk_fma_f32 v[196:197], v[196:197], v[176:177], v[174:175]
	v_pk_add_f32 v[190:191], v[174:175], v[190:191]
	v_pk_add_f32 v[192:193], v[174:175], v[192:193]
	v_pk_add_f32 v[194:195], v[174:175], v[194:195]
	v_pk_add_f32 v[196:197], v[174:175], v[196:197]
	v_pk_mul_f32 v[56:57], v[56:57], v[190:191]
	v_pk_mul_f32 v[58:59], v[58:59], v[192:193]
	v_pk_mul_f32 v[60:61], v[60:61], v[194:195]
	v_pk_mul_f32 v[62:63], v[62:63], v[196:197]
	v_cvt_pk_bf16_f32 v202, v56, v57
	v_cvt_pk_bf16_f32 v203, v58, v59
	v_cvt_pk_bf16_f32 v204, v60, v61
	v_cvt_pk_bf16_f32 v205, v62, v63
	s_nop 1
	v_permlane32_swap_b32 v202, v204
	v_permlane32_swap_b32 v203, v205
	global_store_dwordx4 v[236:237], v[202:205], off offset:1024
	v_pk_mul_f32 v[190:191], v[166:167], v[16:17]
	v_pk_mul_f32 v[192:193], v[166:167], v[18:19]
	v_pk_mul_f32 v[194:195], v[166:167], v[20:21]
	v_pk_mul_f32 v[196:197], v[166:167], v[22:23]
	v_pk_mul_f32 v[190:191], v[16:17], v[190:191]
	v_pk_mul_f32 v[192:193], v[18:19], v[192:193]
	v_pk_mul_f32 v[194:195], v[20:21], v[194:195]
	v_pk_mul_f32 v[196:197], v[22:23], v[196:197]
	v_pk_fma_f32 v[190:191], v[16:17], v[190:191], v[16:17]
	v_pk_fma_f32 v[192:193], v[18:19], v[192:193], v[18:19]
	v_pk_fma_f32 v[194:195], v[20:21], v[194:195], v[20:21]
	v_pk_fma_f32 v[196:197], v[22:23], v[196:197], v[22:23]
	v_pk_mul_f32 v[190:191], v[168:169], v[190:191]
	v_pk_mul_f32 v[192:193], v[168:169], v[192:193]
	v_pk_mul_f32 v[194:195], v[168:169], v[194:195]
	v_pk_mul_f32 v[196:197], v[168:169], v[196:197]
	v_pk_add_f32 v[190:191], v[190:191], v[190:191]
	v_pk_add_f32 v[192:193], v[192:193], v[192:193]
	v_pk_add_f32 v[194:195], v[194:195], v[194:195]
	v_pk_add_f32 v[196:197], v[196:197], v[196:197]
	v_pk_mul_f32 v[190:191], v[170:171], v[190:191]
	v_pk_mul_f32 v[192:193], v[170:171], v[192:193]
	v_pk_mul_f32 v[194:195], v[170:171], v[194:195]
	v_pk_mul_f32 v[196:197], v[170:171], v[196:197]
	v_exp_f32_e32 v190, v190
	v_exp_f32_e32 v191, v191
	v_exp_f32_e32 v192, v192
	v_exp_f32_e32 v193, v193
	v_exp_f32_e32 v194, v194
	v_exp_f32_e32 v195, v195
	v_exp_f32_e32 v196, v196
	v_exp_f32_e32 v197, v197
	v_pk_mul_f32 v[16:17], v[172:173], v[16:17]
	v_pk_mul_f32 v[18:19], v[172:173], v[18:19]
	v_pk_mul_f32 v[20:21], v[172:173], v[20:21]
	v_pk_mul_f32 v[22:23], v[172:173], v[22:23]
	v_pk_add_f32 v[190:191], v[174:175], v[190:191]
	v_pk_add_f32 v[192:193], v[174:175], v[192:193]
	v_pk_add_f32 v[194:195], v[174:175], v[194:195]
	v_pk_add_f32 v[196:197], v[174:175], v[196:197]
	v_rcp_f32_e32 v190, v190
	v_rcp_f32_e32 v191, v191
	v_rcp_f32_e32 v192, v192
	v_rcp_f32_e32 v193, v193
	v_rcp_f32_e32 v194, v194
	v_rcp_f32_e32 v195, v195
	v_rcp_f32_e32 v196, v196
	v_rcp_f32_e32 v197, v197
	s_nop 0
	v_pk_fma_f32 v[190:191], v[190:191], v[176:177], v[174:175]
	v_pk_fma_f32 v[192:193], v[192:193], v[176:177], v[174:175]
	v_pk_fma_f32 v[194:195], v[194:195], v[176:177], v[174:175]
	v_pk_fma_f32 v[196:197], v[196:197], v[176:177], v[174:175]
	v_pk_add_f32 v[190:191], v[174:175], v[190:191]
	v_pk_add_f32 v[192:193], v[174:175], v[192:193]
	v_pk_add_f32 v[194:195], v[174:175], v[194:195]
	v_pk_add_f32 v[196:197], v[174:175], v[196:197]
	v_pk_mul_f32 v[16:17], v[16:17], v[190:191]
	v_pk_mul_f32 v[18:19], v[18:19], v[192:193]
	v_pk_mul_f32 v[20:21], v[20:21], v[194:195]
	v_pk_mul_f32 v[22:23], v[22:23], v[196:197]
	v_cvt_pk_bf16_f32 v198, v16, v17
	v_cvt_pk_bf16_f32 v199, v18, v19
	v_cvt_pk_bf16_f32 v200, v20, v21
	v_cvt_pk_bf16_f32 v201, v22, v23
	s_nop 1
	v_permlane32_swap_b32 v198, v200
	v_permlane32_swap_b32 v199, v201
	global_store_dwordx4 v[238:239], v[198:201], off
	v_pk_mul_f32 v[190:191], v[166:167], v[24:25]
	v_pk_mul_f32 v[192:193], v[166:167], v[26:27]
	v_pk_mul_f32 v[194:195], v[166:167], v[28:29]
	v_pk_mul_f32 v[196:197], v[166:167], v[30:31]
	v_pk_mul_f32 v[190:191], v[24:25], v[190:191]
	v_pk_mul_f32 v[192:193], v[26:27], v[192:193]
	v_pk_mul_f32 v[194:195], v[28:29], v[194:195]
	v_pk_mul_f32 v[196:197], v[30:31], v[196:197]
	v_pk_fma_f32 v[190:191], v[24:25], v[190:191], v[24:25]
	v_pk_fma_f32 v[192:193], v[26:27], v[192:193], v[26:27]
	v_pk_fma_f32 v[194:195], v[28:29], v[194:195], v[28:29]
	v_pk_fma_f32 v[196:197], v[30:31], v[196:197], v[30:31]
	v_pk_mul_f32 v[190:191], v[168:169], v[190:191]
	v_pk_mul_f32 v[192:193], v[168:169], v[192:193]
	v_pk_mul_f32 v[194:195], v[168:169], v[194:195]
	v_pk_mul_f32 v[196:197], v[168:169], v[196:197]
	v_pk_add_f32 v[190:191], v[190:191], v[190:191]
	v_pk_add_f32 v[192:193], v[192:193], v[192:193]
	v_pk_add_f32 v[194:195], v[194:195], v[194:195]
	v_pk_add_f32 v[196:197], v[196:197], v[196:197]
	v_pk_mul_f32 v[190:191], v[170:171], v[190:191]
	v_pk_mul_f32 v[192:193], v[170:171], v[192:193]
	v_pk_mul_f32 v[194:195], v[170:171], v[194:195]
	v_pk_mul_f32 v[196:197], v[170:171], v[196:197]
	v_exp_f32_e32 v190, v190
	v_exp_f32_e32 v191, v191
	v_exp_f32_e32 v192, v192
	v_exp_f32_e32 v193, v193
	v_exp_f32_e32 v194, v194
	v_exp_f32_e32 v195, v195
	v_exp_f32_e32 v196, v196
	v_exp_f32_e32 v197, v197
	v_pk_mul_f32 v[24:25], v[172:173], v[24:25]
	v_pk_mul_f32 v[26:27], v[172:173], v[26:27]
	v_pk_mul_f32 v[28:29], v[172:173], v[28:29]
	v_pk_mul_f32 v[30:31], v[172:173], v[30:31]
	v_pk_add_f32 v[190:191], v[174:175], v[190:191]
	v_pk_add_f32 v[192:193], v[174:175], v[192:193]
	v_pk_add_f32 v[194:195], v[174:175], v[194:195]
	v_pk_add_f32 v[196:197], v[174:175], v[196:197]
	v_rcp_f32_e32 v190, v190
	v_rcp_f32_e32 v191, v191
	v_rcp_f32_e32 v192, v192
	v_rcp_f32_e32 v193, v193
	v_rcp_f32_e32 v194, v194
	v_rcp_f32_e32 v195, v195
	v_rcp_f32_e32 v196, v196
	v_rcp_f32_e32 v197, v197
	s_nop 0
	v_pk_fma_f32 v[190:191], v[190:191], v[176:177], v[174:175]
	v_pk_fma_f32 v[192:193], v[192:193], v[176:177], v[174:175]
	v_pk_fma_f32 v[194:195], v[194:195], v[176:177], v[174:175]
	v_pk_fma_f32 v[196:197], v[196:197], v[176:177], v[174:175]
	v_pk_add_f32 v[190:191], v[174:175], v[190:191]
	v_pk_add_f32 v[192:193], v[174:175], v[192:193]
	v_pk_add_f32 v[194:195], v[174:175], v[194:195]
	v_pk_add_f32 v[196:197], v[174:175], v[196:197]
	v_pk_mul_f32 v[24:25], v[24:25], v[190:191]
	v_pk_mul_f32 v[26:27], v[26:27], v[192:193]
	v_pk_mul_f32 v[28:29], v[28:29], v[194:195]
	v_pk_mul_f32 v[30:31], v[30:31], v[196:197]
	v_cvt_pk_bf16_f32 v202, v24, v25
	v_cvt_pk_bf16_f32 v203, v26, v27
	v_cvt_pk_bf16_f32 v204, v28, v29
	v_cvt_pk_bf16_f32 v205, v30, v31
	s_nop 1
	v_permlane32_swap_b32 v202, v204
	v_permlane32_swap_b32 v203, v205
	global_store_dwordx4 v[238:239], v[202:205], off offset:1024
	v_pk_mul_f32 v[190:191], v[166:167], v[0:1]
	v_pk_mul_f32 v[192:193], v[166:167], v[2:3]
	v_pk_mul_f32 v[194:195], v[166:167], v[4:5]
	v_pk_mul_f32 v[196:197], v[166:167], v[6:7]
	v_pk_mul_f32 v[190:191], v[0:1], v[190:191]
	v_pk_mul_f32 v[192:193], v[2:3], v[192:193]
	v_pk_mul_f32 v[194:195], v[4:5], v[194:195]
	v_pk_mul_f32 v[196:197], v[6:7], v[196:197]
	v_pk_fma_f32 v[190:191], v[0:1], v[190:191], v[0:1]
	v_pk_fma_f32 v[192:193], v[2:3], v[192:193], v[2:3]
	v_pk_fma_f32 v[194:195], v[4:5], v[194:195], v[4:5]
	v_pk_fma_f32 v[196:197], v[6:7], v[196:197], v[6:7]
	v_pk_mul_f32 v[190:191], v[168:169], v[190:191]
	v_pk_mul_f32 v[192:193], v[168:169], v[192:193]
	v_pk_mul_f32 v[194:195], v[168:169], v[194:195]
	v_pk_mul_f32 v[196:197], v[168:169], v[196:197]
	v_pk_add_f32 v[190:191], v[190:191], v[190:191]
	v_pk_add_f32 v[192:193], v[192:193], v[192:193]
	v_pk_add_f32 v[194:195], v[194:195], v[194:195]
	v_pk_add_f32 v[196:197], v[196:197], v[196:197]
	v_pk_mul_f32 v[190:191], v[170:171], v[190:191]
	v_pk_mul_f32 v[192:193], v[170:171], v[192:193]
	v_pk_mul_f32 v[194:195], v[170:171], v[194:195]
	v_pk_mul_f32 v[196:197], v[170:171], v[196:197]
	v_exp_f32_e32 v190, v190
	v_exp_f32_e32 v191, v191
	v_exp_f32_e32 v192, v192
	v_exp_f32_e32 v193, v193
	v_exp_f32_e32 v194, v194
	v_exp_f32_e32 v195, v195
	v_exp_f32_e32 v196, v196
	v_exp_f32_e32 v197, v197
	v_pk_mul_f32 v[0:1], v[172:173], v[0:1]
	v_pk_mul_f32 v[2:3], v[172:173], v[2:3]
	v_pk_mul_f32 v[4:5], v[172:173], v[4:5]
	v_pk_mul_f32 v[6:7], v[172:173], v[6:7]
	v_pk_add_f32 v[190:191], v[174:175], v[190:191]
	v_pk_add_f32 v[192:193], v[174:175], v[192:193]
	v_pk_add_f32 v[194:195], v[174:175], v[194:195]
	v_pk_add_f32 v[196:197], v[174:175], v[196:197]
	v_rcp_f32_e32 v190, v190
	v_rcp_f32_e32 v191, v191
	v_rcp_f32_e32 v192, v192
	v_rcp_f32_e32 v193, v193
	v_rcp_f32_e32 v194, v194
	v_rcp_f32_e32 v195, v195
	v_rcp_f32_e32 v196, v196
	v_rcp_f32_e32 v197, v197
	s_nop 0
	v_pk_fma_f32 v[190:191], v[190:191], v[176:177], v[174:175]
	v_pk_fma_f32 v[192:193], v[192:193], v[176:177], v[174:175]
	v_pk_fma_f32 v[194:195], v[194:195], v[176:177], v[174:175]
	v_pk_fma_f32 v[196:197], v[196:197], v[176:177], v[174:175]
	v_pk_add_f32 v[190:191], v[174:175], v[190:191]
	v_pk_add_f32 v[192:193], v[174:175], v[192:193]
	v_pk_add_f32 v[194:195], v[174:175], v[194:195]
	v_pk_add_f32 v[196:197], v[174:175], v[196:197]
	v_pk_mul_f32 v[0:1], v[0:1], v[190:191]
	v_pk_mul_f32 v[2:3], v[2:3], v[192:193]
	v_pk_mul_f32 v[4:5], v[4:5], v[194:195]
	v_pk_mul_f32 v[6:7], v[6:7], v[196:197]
	v_cvt_pk_bf16_f32 v198, v0, v1
	v_cvt_pk_bf16_f32 v199, v2, v3
	v_cvt_pk_bf16_f32 v200, v4, v5
	v_cvt_pk_bf16_f32 v201, v6, v7
	s_nop 1
	v_permlane32_swap_b32 v198, v200
	v_permlane32_swap_b32 v199, v201
	global_store_dwordx4 v[240:241], v[198:201], off
	v_pk_mul_f32 v[190:191], v[166:167], v[8:9]
	v_pk_mul_f32 v[192:193], v[166:167], v[10:11]
	v_pk_mul_f32 v[194:195], v[166:167], v[12:13]
	v_pk_mul_f32 v[196:197], v[166:167], v[14:15]
	v_pk_mul_f32 v[190:191], v[8:9], v[190:191]
	v_pk_mul_f32 v[192:193], v[10:11], v[192:193]
	v_pk_mul_f32 v[194:195], v[12:13], v[194:195]
	v_pk_mul_f32 v[196:197], v[14:15], v[196:197]
	v_pk_fma_f32 v[190:191], v[8:9], v[190:191], v[8:9]
	v_pk_fma_f32 v[192:193], v[10:11], v[192:193], v[10:11]
	v_pk_fma_f32 v[194:195], v[12:13], v[194:195], v[12:13]
	v_pk_fma_f32 v[196:197], v[14:15], v[196:197], v[14:15]
	v_pk_mul_f32 v[190:191], v[168:169], v[190:191]
	v_pk_mul_f32 v[192:193], v[168:169], v[192:193]
	v_pk_mul_f32 v[194:195], v[168:169], v[194:195]
	v_pk_mul_f32 v[196:197], v[168:169], v[196:197]
	v_pk_add_f32 v[190:191], v[190:191], v[190:191]
	v_pk_add_f32 v[192:193], v[192:193], v[192:193]
	v_pk_add_f32 v[194:195], v[194:195], v[194:195]
	v_pk_add_f32 v[196:197], v[196:197], v[196:197]
	v_pk_mul_f32 v[190:191], v[170:171], v[190:191]
	v_pk_mul_f32 v[192:193], v[170:171], v[192:193]
	v_pk_mul_f32 v[194:195], v[170:171], v[194:195]
	v_pk_mul_f32 v[196:197], v[170:171], v[196:197]
	v_exp_f32_e32 v190, v190
	v_exp_f32_e32 v191, v191
	v_exp_f32_e32 v192, v192
	v_exp_f32_e32 v193, v193
	v_exp_f32_e32 v194, v194
	v_exp_f32_e32 v195, v195
	v_exp_f32_e32 v196, v196
	v_exp_f32_e32 v197, v197
	v_pk_mul_f32 v[8:9], v[172:173], v[8:9]
	v_pk_mul_f32 v[10:11], v[172:173], v[10:11]
	v_pk_mul_f32 v[12:13], v[172:173], v[12:13]
	v_pk_mul_f32 v[14:15], v[172:173], v[14:15]
	v_pk_add_f32 v[190:191], v[174:175], v[190:191]
	v_pk_add_f32 v[192:193], v[174:175], v[192:193]
	v_pk_add_f32 v[194:195], v[174:175], v[194:195]
	v_pk_add_f32 v[196:197], v[174:175], v[196:197]
	v_rcp_f32_e32 v190, v190
	v_rcp_f32_e32 v191, v191
	v_rcp_f32_e32 v192, v192
	v_rcp_f32_e32 v193, v193
	v_rcp_f32_e32 v194, v194
	v_rcp_f32_e32 v195, v195
	v_rcp_f32_e32 v196, v196
	v_rcp_f32_e32 v197, v197
	s_nop 0
	v_pk_fma_f32 v[190:191], v[190:191], v[176:177], v[174:175]
	v_pk_fma_f32 v[192:193], v[192:193], v[176:177], v[174:175]
	v_pk_fma_f32 v[194:195], v[194:195], v[176:177], v[174:175]
	v_pk_fma_f32 v[196:197], v[196:197], v[176:177], v[174:175]
	v_pk_add_f32 v[190:191], v[174:175], v[190:191]
	v_pk_add_f32 v[192:193], v[174:175], v[192:193]
	v_pk_add_f32 v[194:195], v[174:175], v[194:195]
	v_pk_add_f32 v[196:197], v[174:175], v[196:197]
	v_pk_mul_f32 v[8:9], v[8:9], v[190:191]
	v_pk_mul_f32 v[10:11], v[10:11], v[192:193]
	v_pk_mul_f32 v[12:13], v[12:13], v[194:195]
	v_pk_mul_f32 v[14:15], v[14:15], v[196:197]
	v_cvt_pk_bf16_f32 v202, v8, v9
	v_cvt_pk_bf16_f32 v203, v10, v11
	v_cvt_pk_bf16_f32 v204, v12, v13
	v_cvt_pk_bf16_f32 v205, v14, v15
	s_nop 1
	v_permlane32_swap_b32 v202, v204
	v_permlane32_swap_b32 v203, v205
	global_store_dwordx4 v[240:241], v[202:205], off offset:1024
	s_cmpk_gt_i32 s6, 0x1ff
	s_cbranch_scc0 .LBB0_718
